# stack5 + all bit-identical attention-loop trims together (slim LDS-DMA blocks, redundant QK-phase waits, row-max chain trims, fox packed-add split)
# speedup vs baseline: 1.0165x; 1.0165x over previous
.LBB0_251:
	v_add_u32_e32 v0, s18, v225
	ds_read_b64_tr_b16 v[192:193], v0 offset:24576
	ds_read_b64_tr_b16 v[194:195], v0 offset:25088
	v_add_f32_e32 v2, v80, v81
	v_add_f32_e32 v2, v82, v2
	v_add_f32_e32 v2, v83, v2
	v_add_f32_e32 v2, v84, v2
	v_add_f32_e32 v2, v85, v2
	v_cvt_pk_bf16_f32 v156, v80, v81
	v_cvt_pk_bf16_f32 v157, v82, v83
	s_waitcnt lgkmcnt(9)
	v_mfma_f32_32x32x16_bf16 v[96:111], v[188:191], v[140:143], v[48:63]
	ds_read_b64_tr_b16 v[188:189], v0 offset:28672
	ds_read_b64_tr_b16 v[190:191], v0 offset:29184
	v_add_f32_e32 v2, v86, v2
	v_add_f32_e32 v2, v87, v2
	v_add_f32_e32 v2, v88, v2
	v_add_f32_e32 v2, v89, v2
	v_cvt_pk_bf16_f32 v158, v84, v85
	v_cvt_pk_bf16_f32 v159, v86, v87
	s_waitcnt lgkmcnt(10)
	v_mfma_f32_32x32x16_bf16 v[112:127], v[184:187], v[140:143], v[48:63]
	ds_read_b64_tr_b16 v[10:11], v0 offset:25600
	ds_read_b64_tr_b16 v[12:13], v0 offset:26112
	v_add_f32_e32 v2, v90, v2
	v_add_f32_e32 v2, v91, v2
	v_add_f32_e32 v2, v92, v2
	v_add_f32_e32 v2, v93, v2
	v_cvt_pk_bf16_f32 v152, v88, v89
	v_cvt_pk_bf16_f32 v153, v90, v91
	s_waitcnt lgkmcnt(11)
	v_mfma_f32_32x32x16_bf16 v[96:111], v[180:183], v[136:139], v[96:111]
	ds_read_b64_tr_b16 v[180:181], v0 offset:29696
	ds_read_b64_tr_b16 v[182:183], v0 offset:30208
	v_add_f32_e32 v2, v94, v2
	v_add_f32_e32 v2, v95, v2
	v_add_f32_e32 v2, v64, v2
	v_add_f32_e32 v2, v65, v2
	v_cvt_pk_bf16_f32 v154, v92, v93
	v_cvt_pk_bf16_f32 v155, v94, v95
	s_waitcnt lgkmcnt(12)
	v_mfma_f32_32x32x16_bf16 v[112:127], v[176:179], v[136:139], v[112:127]
	ds_read_b64_tr_b16 v[176:177], v0 offset:26624
	ds_read_b64_tr_b16 v[178:179], v0 offset:27136
	v_add_f32_e32 v2, v66, v2
	v_add_f32_e32 v2, v67, v2
	v_add_f32_e32 v2, v68, v2
	v_add_f32_e32 v6, v69, v2
	v_cvt_pk_bf16_f32 v148, v64, v65
	v_cvt_pk_bf16_f32 v149, v66, v67
	s_waitcnt lgkmcnt(13)
	v_mfma_f32_32x32x16_bf16 v[96:111], v[172:175], v[132:135], v[96:111]
	ds_read_b64_tr_b16 v[2:3], v0 offset:30720
	ds_read_b64_tr_b16 v[4:5], v0 offset:31232
	v_add_f32_e32 v6, v70, v6
	v_add_f32_e32 v6, v71, v6
	v_add_f32_e32 v6, v72, v6
	v_add_f32_e32 v14, v73, v6
	v_cvt_pk_bf16_f32 v150, v68, v69
	v_cvt_pk_bf16_f32 v151, v70, v71
	s_waitcnt lgkmcnt(14)
	v_mfma_f32_32x32x16_bf16 v[112:127], v[168:171], v[132:135], v[112:127]
	ds_read_b64_tr_b16 v[6:7], v0 offset:27648
	ds_read_b64_tr_b16 v[8:9], v0 offset:28160
	v_add_f32_e32 v14, v74, v14
	v_add_f32_e32 v14, v75, v14
	v_add_f32_e32 v14, v76, v14
	v_add_f32_e32 v14, v77, v14
	v_cvt_pk_bf16_f32 v144, v72, v73
	v_cvt_pk_bf16_f32 v145, v74, v75
	s_waitcnt lgkmcnt(14)
	v_mfma_f32_32x32x16_bf16 v[96:111], v[164:167], v[128:131], v[96:111]
	ds_read_b64_tr_b16 v[164:165], v0 offset:31744
	ds_read_b64_tr_b16 v[166:167], v0 offset:32256
	v_add_f32_e32 v0, v78, v14
	v_add_f32_e32 v0, v79, v0
	v_add_f32_e32 v0, 0, v0
	v_cvt_pk_bf16_f32 v146, v76, v77
	v_cvt_pk_bf16_f32 v147, v78, v79
	v_mfma_f32_32x32x16_bf16 v[112:127], v[160:163], v[128:131], v[112:127]
	v_lshl_add_u64 v[14:15], v[202:203], 0, s[54:55]
	s_add_i32 s18, s69, s38
	s_mov_b32 m0, s18
	s_nop 0
	global_load_lds_dwordx4 v[14:15], off
	v_lshl_add_u64 v[14:15], v[200:201], 0, s[54:55]
	s_add_i32 s18, s7, s59
	s_mov_b32 m0, s18
	s_nop 0
	global_load_lds_dwordx4 v[14:15], off
	ds_read_b128 v[64:67], v204
	ds_read_b128 v[68:71], v204 offset:32
	ds_read_b128 v[72:75], v204 offset:128
	v_add_f32_e32 v0, v230, v0
	s_waitcnt lgkmcnt(2)
	v_add_f32_e32 v82, v98, v66
	v_add_f32_e32 v83, v99, v67
	s_waitcnt lgkmcnt(1)
	v_add_f32_e32 v84, v100, v68
	v_add_f32_e32 v85, v101, v69
	s_waitcnt lgkmcnt(0)
	v_add_f32_e32 v14, v112, v72
	v_add_f32_e32 v15, v113, v73
	v_add_f32_e32 v66, v114, v74
	v_add_f32_e32 v67, v115, v75
	ds_read_b128 v[72:75], v204 offset:160
	v_add_f32_e32 v86, v102, v70
	v_add_f32_e32 v87, v103, v71
	v_add_f32_e32 v64, v96, v64
	v_add_f32_e32 v65, v97, v65
	v_max3_f32 v81, v82, v83, v15
	v_max_f32_e32 v80, v64, v65
	s_waitcnt lgkmcnt(0)
	v_add_f32_e32 v68, v116, v72
	v_add_f32_e32 v69, v117, v73
	v_add_f32_e32 v70, v118, v74
	v_add_f32_e32 v71, v119, v75
	ds_read_b128 v[72:75], v204 offset:64
	ds_read_b128 v[76:79], v204 offset:192
	v_max3_f32 v80, v80, v14, v66
	v_max3_f32 v80, v80, v67, v84
	v_max3_f32 v81, v81, v86, v87
	s_waitcnt lgkmcnt(1)
	v_add_f32_e32 v88, v104, v72
	v_add_f32_e32 v89, v105, v73
	s_waitcnt lgkmcnt(0)
	v_add_f32_e32 v72, v120, v76
	v_add_f32_e32 v73, v121, v77
	v_add_f32_e32 v90, v106, v74
	v_add_f32_e32 v91, v107, v75
	v_add_f32_e32 v74, v122, v78
	v_add_f32_e32 v75, v123, v79
	ds_read_b128 v[76:79], v204 offset:96
	ds_read_b128 v[94:97], v204 offset:224
	v_max3_f32 v80, v80, v85, v68
	v_max3_f32 v81, v81, v70, v71
	v_max3_f32 v80, v80, v69, v88
	v_max3_f32 v81, v81, v90, v91
	s_waitcnt lgkmcnt(1)
	v_add_f32_e32 v92, v108, v76
	v_add_f32_e32 v93, v109, v77
	s_waitcnt lgkmcnt(0)
	v_add_f32_e32 v76, v124, v94
	v_add_f32_e32 v77, v125, v95
	v_add_f32_e32 v94, v110, v78
	v_add_f32_e32 v95, v111, v79
	v_max3_f32 v80, v80, v89, v72
	v_max3_f32 v81, v81, v74, v75
	v_add_f32_e32 v78, v126, v96
	v_add_f32_e32 v79, v127, v97
	v_max3_f32 v80, v80, v73, v92
	v_max3_f32 v81, v81, v94, v95
	v_max3_f32 v80, v80, v93, v76
	v_max3_f32 v81, v81, v78, v79
	v_max3_f32 v80, v80, v77, v81
	v_mov_b32_e32 v81, v80
	s_nop 1
	v_permlane32_swap_b32_e32 v80, v81
	v_max_f32_e32 v80, v80, v81
	v_cmp_lt_f32_e32 vcc, s96, v80
	s_cmp_lg_u64 vcc, 0
	s_cselect_b64 s[18:19], -1, 0
	s_cbranch_vccnz .LBB0_259

.LBB0_254:
	s_add_i32 s18, s7, 0x2000
	s_cmpk_lg_i32 s7, 0x4000
	s_cselect_b32 s60, s18, 0
	v_add_u32_e32 v14, s69, v225
	ds_read_b64_tr_b16 v[168:169], v14 offset:24576
	ds_read_b64_tr_b16 v[170:171], v14 offset:25088
	v_add_f32_e32 v2, v80, v81
	v_add_f32_e32 v2, v82, v2
	v_add_f32_e32 v2, v83, v2
	v_add_f32_e32 v2, v84, v2
	v_add_f32_e32 v2, v85, v2
	v_cvt_pk_bf16_f32 v156, v80, v81
	v_cvt_pk_bf16_f32 v157, v82, v83
	s_waitcnt lgkmcnt(9)
	v_mfma_f32_32x32x16_bf16 v[96:111], v[112:115], v[140:143], v[48:63]
	ds_read_b64_tr_b16 v[164:165], v14 offset:28672
	ds_read_b64_tr_b16 v[166:167], v14 offset:29184
	v_add_f32_e32 v2, v86, v2
	v_add_f32_e32 v2, v87, v2
	v_add_f32_e32 v2, v88, v2
	v_add_f32_e32 v2, v89, v2
	v_cvt_pk_bf16_f32 v158, v84, v85
	v_cvt_pk_bf16_f32 v159, v86, v87
	s_waitcnt lgkmcnt(10)
	v_mfma_f32_32x32x16_bf16 v[112:127], v[160:163], v[140:143], v[48:63]
	ds_read_b64_tr_b16 v[10:11], v14 offset:25600
	ds_read_b64_tr_b16 v[12:13], v14 offset:26112
	v_add_f32_e32 v2, v90, v2
	v_add_f32_e32 v2, v91, v2
	v_add_f32_e32 v2, v92, v2
	v_add_f32_e32 v2, v93, v2
	v_cvt_pk_bf16_f32 v152, v88, v89
	v_cvt_pk_bf16_f32 v153, v90, v91
	s_waitcnt lgkmcnt(11)
	v_mfma_f32_32x32x16_bf16 v[96:111], v[192:195], v[136:139], v[96:111]
	ds_read_b64_tr_b16 v[160:161], v14 offset:29696
	ds_read_b64_tr_b16 v[162:163], v14 offset:30208
	v_add_f32_e32 v2, v94, v2
	v_add_f32_e32 v2, v95, v2
	v_add_f32_e32 v2, v64, v2
	v_add_f32_e32 v2, v65, v2
	v_cvt_pk_bf16_f32 v154, v92, v93
	v_cvt_pk_bf16_f32 v155, v94, v95
	s_waitcnt lgkmcnt(12)
	v_mfma_f32_32x32x16_bf16 v[112:127], v[188:191], v[136:139], v[112:127]
	ds_read_b64_tr_b16 v[196:197], v14 offset:26624
	ds_read_b64_tr_b16 v[198:199], v14 offset:27136
	v_add_f32_e32 v2, v66, v2
	v_add_f32_e32 v2, v67, v2
	v_add_f32_e32 v2, v68, v2
	v_add_f32_e32 v6, v69, v2
	v_cvt_pk_bf16_f32 v148, v64, v65
	v_cvt_pk_bf16_f32 v149, v66, v67
	s_waitcnt lgkmcnt(13)
	v_mfma_f32_32x32x16_bf16 v[96:111], v[184:187], v[132:135], v[96:111]
	ds_read_b64_tr_b16 v[2:3], v14 offset:30720
	ds_read_b64_tr_b16 v[4:5], v14 offset:31232
	v_add_f32_e32 v6, v70, v6
	v_add_f32_e32 v6, v71, v6
	v_add_f32_e32 v6, v72, v6
	v_add_f32_e32 v15, v73, v6
	v_cvt_pk_bf16_f32 v150, v68, v69
	v_cvt_pk_bf16_f32 v151, v70, v71
	s_waitcnt lgkmcnt(14)
	v_mfma_f32_32x32x16_bf16 v[112:127], v[180:183], v[132:135], v[112:127]
	ds_read_b64_tr_b16 v[6:7], v14 offset:27648
	ds_read_b64_tr_b16 v[8:9], v14 offset:28160
	v_add_f32_e32 v15, v74, v15
	v_add_f32_e32 v15, v75, v15
	v_add_f32_e32 v15, v76, v15
	v_add_f32_e32 v15, v77, v15
	v_cvt_pk_bf16_f32 v144, v72, v73
	v_cvt_pk_bf16_f32 v145, v74, v75
	s_waitcnt lgkmcnt(14)
	v_mfma_f32_32x32x16_bf16 v[96:111], v[176:179], v[128:131], v[96:111]
	ds_read_b64_tr_b16 v[192:193], v14 offset:31744
	ds_read_b64_tr_b16 v[194:195], v14 offset:32256
	v_add_f32_e32 v14, v78, v15
	v_add_f32_e32 v14, v79, v14
	v_add_f32_e32 v80, 0, v14
	v_cvt_pk_bf16_f32 v146, v76, v77
	v_cvt_pk_bf16_f32 v147, v78, v79
	v_mfma_f32_32x32x16_bf16 v[112:127], v[172:175], v[128:131], v[112:127]
	s_add_i32 s18, s7, s38
	s_mov_b32 m0, s18
	s_nop 0
	global_load_lds_dwordx4 v[202:203], off
	s_add_i32 s18, s60, s59
	s_mov_b32 m0, s18
	s_nop 0
	global_load_lds_dwordx4 v[200:201], off
	ds_read_b128 v[64:67], v204 offset:256
	ds_read_b128 v[68:71], v204 offset:288
	ds_read_b128 v[72:75], v204 offset:384
	v_add_f32_e32 v230, v0, v80
	s_waitcnt lgkmcnt(2)
	v_add_f32_e32 v82, v98, v66
	v_add_f32_e32 v83, v99, v67
	s_waitcnt lgkmcnt(1)
	v_add_f32_e32 v84, v100, v68
	v_add_f32_e32 v85, v101, v69
	s_waitcnt lgkmcnt(0)
	s_nop 0
	v_add_f32_e32 v14, v112, v72
	v_add_f32_e32 v15, v113, v73
	v_add_f32_e32 v66, v114, v74
	v_add_f32_e32 v67, v115, v75
	ds_read_b128 v[72:75], v204 offset:416
	v_add_f32_e32 v86, v102, v70
	v_add_f32_e32 v87, v103, v71
	v_add_f32_e32 v64, v96, v64
	v_add_f32_e32 v65, v97, v65
	s_waitcnt lgkmcnt(0)
	v_add_f32_e32 v68, v116, v72
	v_add_f32_e32 v69, v117, v73
	v_add_f32_e32 v70, v118, v74
	v_add_f32_e32 v71, v119, v75
	ds_read_b128 v[72:75], v204 offset:320
	ds_read_b128 v[76:79], v204 offset:448
	v_max_f32_e32 v81, v64, v65
	v_max3_f32 v81, v81, v14, v66
	v_max3_f32 v81, v81, v67, v84
	s_waitcnt lgkmcnt(1)
	v_add_f32_e32 v88, v104, v72
	v_add_f32_e32 v89, v105, v73
	s_waitcnt lgkmcnt(0)
	v_add_f32_e32 v72, v120, v76
	v_add_f32_e32 v73, v121, v77
	v_add_f32_e32 v90, v106, v74
	v_add_f32_e32 v91, v107, v75
	v_add_f32_e32 v74, v122, v78
	v_add_f32_e32 v75, v123, v79
	ds_read_b128 v[76:79], v204 offset:352
	ds_read_b128 v[94:97], v204 offset:480
	v_max3_f32 v81, v81, v85, v68
	v_max3_f32 v81, v81, v69, v88
	v_max3_f32 v81, v81, v89, v72
	s_waitcnt lgkmcnt(1)
	v_add_f32_e32 v92, v108, v76
	v_add_f32_e32 v93, v109, v77
	s_waitcnt lgkmcnt(0)
	v_add_f32_e32 v76, v124, v94
	v_add_f32_e32 v77, v125, v95
	v_add_f32_e32 v94, v110, v78
	v_add_f32_e32 v95, v111, v79
	v_add_f32_e32 v78, v126, v96
	v_add_f32_e32 v79, v127, v97
	v_max3_f32 v96, v82, v83, v15
	v_max3_f32 v96, v96, v86, v87
	v_max3_f32 v96, v96, v70, v71
	v_max3_f32 v96, v96, v90, v91
	v_max3_f32 v96, v96, v74, v75
	v_max3_f32 v81, v81, v73, v92
	v_max3_f32 v96, v96, v94, v95
	v_max3_f32 v81, v81, v93, v76
	v_max3_f32 v96, v96, v78, v79
	v_max3_f32 v0, v81, v77, v96
	v_mov_b32_e32 v80, v0
	s_nop 1
	v_permlane32_swap_b32_e32 v0, v80
	v_max_f32_e32 v0, v0, v80
	v_cmp_lt_f32_e32 vcc, s96, v0
	s_cmp_lg_u64 vcc, 0
	s_cselect_b64 s[18:19], -1, 0
	s_cbranch_vccnz .LBB0_262

.LBB0_280:
	v_mfma_f32_32x32x16_bf16 v[144:159], v[220:223], v[184:187], v[80:95]
	v_add_f32_e32 v2, v112, v113
	v_add_f32_e32 v2, v114, v2
	v_add_f32_e32 v2, v115, v2
	s_lshl_b32 s72, s72, 1
	v_add_f32_e32 v2, v116, v2
	v_add_u32_e32 v0, s72, v245
	v_add_f32_e32 v2, v117, v2
	v_cvt_pk_bf16_f32 v188, v112, v113
	v_cvt_pk_bf16_f32 v189, v114, v115
	v_mfma_f32_32x32x16_bf16 v[128:143], v[212:215], v[184:187], v[80:95]
	v_add_f32_e32 v2, v118, v2
	v_add_f32_e32 v2, v119, v2
	v_add_f32_e32 v2, v120, v2
	v_add_f32_e32 v2, v121, v2
	v_cvt_pk_bf16_f32 v190, v116, v117
	v_cvt_pk_bf16_f32 v191, v118, v119
	v_mfma_f32_32x32x16_bf16 v[144:159], v[216:219], v[176:179], v[144:159]
	v_add_f32_e32 v2, v122, v2
	v_add_f32_e32 v2, v123, v2
	v_add_f32_e32 v2, v124, v2
	v_add_f32_e32 v2, v125, v2
	v_cvt_pk_bf16_f32 v180, v120, v121
	v_cvt_pk_bf16_f32 v181, v122, v123
	v_mfma_f32_32x32x16_bf16 v[128:143], v[204:207], v[176:179], v[128:143]
	v_add_f32_e32 v2, v126, v2
	v_add_f32_e32 v2, v127, v2
	v_add_f32_e32 v2, v96, v2
	v_add_f32_e32 v2, v97, v2
	v_cvt_pk_bf16_f32 v182, v124, v125
	v_cvt_pk_bf16_f32 v183, v126, v127
	v_mfma_f32_32x32x16_bf16 v[144:159], v[208:211], v[172:175], v[144:159]
	v_add_f32_e32 v2, v98, v2
	v_add_f32_e32 v2, v99, v2
	v_add_f32_e32 v2, v100, v2
	v_add_f32_e32 v2, v101, v2
	v_cvt_pk_bf16_f32 v168, v96, v97
	v_cvt_pk_bf16_f32 v169, v98, v99
	v_mfma_f32_32x32x16_bf16 v[128:143], v[200:203], v[172:175], v[128:143]
	v_add_f32_e32 v2, v102, v2
	v_add_f32_e32 v2, v103, v2
	v_add_f32_e32 v2, v104, v2
	v_add_f32_e32 v6, v105, v2
	v_cvt_pk_bf16_f32 v170, v100, v101
	v_cvt_pk_bf16_f32 v171, v102, v103
	ds_read_b64_tr_b16 v[2:3], v0 offset:24576
	ds_read_b64_tr_b16 v[4:5], v0 offset:25088
	v_mfma_f32_32x32x16_bf16 v[144:159], v[196:199], v[164:167], v[144:159]
	v_add_f32_e32 v6, v106, v6
	v_add_f32_e32 v6, v107, v6
	v_add_f32_e32 v6, v108, v6
	v_add_f32_e32 v10, v109, v6
	v_cvt_pk_bf16_f32 v160, v104, v105
	v_cvt_pk_bf16_f32 v161, v106, v107
	ds_read_b64_tr_b16 v[6:7], v0 offset:28672
	ds_read_b64_tr_b16 v[8:9], v0 offset:29184
	v_mfma_f32_32x32x16_bf16 v[128:143], v[192:195], v[164:167], v[128:143]
	ds_read_b64_tr_b16 v[100:101], v0 offset:32768
	ds_read_b64_tr_b16 v[102:103], v0 offset:33280
	ds_read_b64_tr_b16 v[104:105], v0 offset:36864
	ds_read_b64_tr_b16 v[106:107], v0 offset:37376
	ds_read_b64_tr_b16 v[112:113], v0 offset:25600
	ds_read_b64_tr_b16 v[114:115], v0 offset:26112
	ds_read_b64_tr_b16 v[116:117], v0 offset:29696
	ds_read_b64_tr_b16 v[118:119], v0 offset:30208
	v_add_f32_e32 v10, v110, v10
	v_add_f32_e32 v10, v111, v10
	v_add_f32_e32 v12, 0, v10
	v_cvt_pk_bf16_f32 v162, v108, v109
	v_cvt_pk_bf16_f32 v163, v110, v111
	s_add_i32 m0, s78, s64
	v_lshl_add_u64 v[14:15], v[234:235], 0, s[6:7]
	v_lshl_add_u64 v[10:11], v[14:15], 0, s[56:57]
	v_lshl_add_u64 v[208:209], v[236:237], 0, s[6:7]
	global_load_lds_dwordx4 v[10:11], off
	s_lshl_b32 s72, s76, 1
	s_add_i32 m0, s72, s63
	v_lshl_add_u64 v[10:11], v[208:209], 0, s[48:49]
	v_lshl_add_u64 v[210:211], v[238:239], 0, s[6:7]
	global_load_lds_dwordx4 v[10:11], off
	s_addk_i32 m0, 0x2000
	v_lshl_add_u64 v[10:11], v[210:211], 0, s[48:49]
	global_load_lds_dwordx4 v[10:11], off
	v_max_f32_e32 v10, v144, v145
	v_max3_f32 v11, v146, v147, v129
	v_max3_f32 v10, v10, v128, v130
	v_max3_f32 v10, v10, v131, v148
	v_max3_f32 v11, v11, v150, v151
	v_max3_f32 v10, v10, v149, v132
	v_max3_f32 v11, v11, v134, v135
	v_max3_f32 v10, v10, v133, v152
	v_max3_f32 v11, v11, v154, v155
	v_max3_f32 v10, v10, v153, v136
	v_max3_f32 v11, v11, v138, v139
	v_max3_f32 v10, v10, v137, v156
	v_max3_f32 v11, v11, v158, v159
	v_max3_f32 v10, v10, v157, v140
	v_max3_f32 v11, v11, v142, v143
	v_max3_f32 v10, v10, v141, v11
	v_mov_b32_e32 v11, v10
	s_nop 1
	v_permlane32_swap_b32_e32 v10, v11
	v_max_f32_e32 v10, v10, v11
	v_cmp_lt_f32_e32 vcc, s96, v10
	s_cmp_lg_u64 vcc, 0
	v_add_f32_e32 v212, v231, v12
	s_cselect_b64 s[72:73], -1, 0
	s_cbranch_vccnz .LBB0_288

.LBB0_283:
	s_add_i32 s72, s76, 0x2000
	s_cmpk_lg_i32 s76, 0x4000
	s_cselect_b32 s87, s72, 0
	v_mfma_f32_32x32x16_bf16 v[112:127], v[96:99], v[184:187], v[80:95]
	v_add_f32_e32 v100, v144, v145
	v_add_f32_e32 v100, v146, v100
	v_add_f32_e32 v100, v147, v100
	s_lshl_b32 s72, s78, 1
	v_add_f32_e32 v100, v148, v100
	v_add_u32_e32 v233, s72, v245
	v_add_f32_e32 v96, v149, v100
	v_cvt_pk_bf16_f32 v188, v144, v145
	v_cvt_pk_bf16_f32 v189, v146, v147
	s_nop 0
	v_add_f32_e32 v96, v150, v96
	v_add_f32_e32 v96, v151, v96
	v_add_f32_e32 v96, v152, v96
	v_add_f32_e32 v144, v153, v96
	v_mfma_f32_32x32x16_bf16 v[96:111], v[10:13], v[184:187], v[80:95]
	v_cvt_pk_bf16_f32 v190, v148, v149
	v_cvt_pk_bf16_f32 v191, v150, v151
	v_mfma_f32_32x32x16_bf16 v[112:127], v[204:207], v[176:179], v[112:127]
	v_add_f32_e32 v10, v154, v144
	v_add_f32_e32 v10, v155, v10
	v_add_f32_e32 v10, v156, v10
	v_add_f32_e32 v10, v157, v10
	v_cvt_pk_bf16_f32 v180, v152, v153
	v_cvt_pk_bf16_f32 v181, v154, v155
	v_mfma_f32_32x32x16_bf16 v[96:111], v[192:195], v[176:179], v[96:111]
	v_add_f32_e32 v10, v158, v10
	v_add_f32_e32 v10, v159, v10
	v_add_f32_e32 v10, v128, v10
	v_add_f32_e32 v10, v129, v10
	v_cvt_pk_bf16_f32 v182, v156, v157
	v_cvt_pk_bf16_f32 v183, v158, v159
	v_mfma_f32_32x32x16_bf16 v[112:127], v[200:203], v[172:175], v[112:127]
	v_add_f32_e32 v10, v130, v10
	v_add_f32_e32 v10, v131, v10
	v_add_f32_e32 v10, v132, v10
	v_add_f32_e32 v10, v133, v10
	v_cvt_pk_bf16_f32 v168, v128, v129
	v_cvt_pk_bf16_f32 v169, v130, v131
	v_mfma_f32_32x32x16_bf16 v[96:111], v[6:9], v[172:175], v[96:111]
	v_add_f32_e32 v6, v134, v10
	v_add_f32_e32 v6, v135, v6
	v_add_f32_e32 v6, v136, v6
	v_add_f32_e32 v10, v137, v6
	v_cvt_pk_bf16_f32 v170, v132, v133
	v_cvt_pk_bf16_f32 v171, v134, v135
	ds_read_b64_tr_b16 v[6:7], v233 offset:24576
	ds_read_b64_tr_b16 v[8:9], v233 offset:25088
	v_mfma_f32_32x32x16_bf16 v[112:127], v[196:199], v[164:167], v[112:127]
	v_add_f32_e32 v10, v138, v10
	v_add_f32_e32 v10, v139, v10
	v_add_f32_e32 v10, v140, v10
	v_add_f32_e32 v128, v141, v10
	v_cvt_pk_bf16_f32 v160, v136, v137
	v_cvt_pk_bf16_f32 v161, v138, v139
	ds_read_b64_tr_b16 v[10:11], v233 offset:28672
	ds_read_b64_tr_b16 v[12:13], v233 offset:29184
	v_mfma_f32_32x32x16_bf16 v[96:111], v[2:5], v[164:167], v[96:111]
	ds_read_b64_tr_b16 v[144:145], v233 offset:32768
	ds_read_b64_tr_b16 v[146:147], v233 offset:33280
	ds_read_b64_tr_b16 v[148:149], v233 offset:36864
	ds_read_b64_tr_b16 v[150:151], v233 offset:37376
	ds_read_b64_tr_b16 v[152:153], v233 offset:25600
	ds_read_b64_tr_b16 v[154:155], v233 offset:26112
	ds_read_b64_tr_b16 v[156:157], v233 offset:29696
	ds_read_b64_tr_b16 v[158:159], v233 offset:30208
	v_add_f32_e32 v2, v142, v128
	v_add_f32_e32 v2, v143, v2
	v_add_f32_e32 v4, 0, v2
	v_cvt_pk_bf16_f32 v162, v140, v141
	v_cvt_pk_bf16_f32 v163, v142, v143
	s_add_i32 m0, s76, s64
	v_lshl_add_u64 v[2:3], v[14:15], 0, s[52:53]
	s_lshl_b32 s72, s87, 1
	global_load_lds_dwordx4 v[2:3], off
	s_add_i32 m0, s72, s63
	v_lshl_add_u64 v[2:3], v[208:209], 0, s[50:51]
	global_load_lds_dwordx4 v[2:3], off
	s_addk_i32 m0, 0x2000
	v_lshl_add_u64 v[2:3], v[210:211], 0, s[50:51]
	global_load_lds_dwordx4 v[2:3], off
	v_max_f32_e32 v2, v112, v113
	v_max3_f32 v3, v114, v115, v97
	v_max3_f32 v2, v2, v96, v98
	v_max3_f32 v2, v2, v99, v116
	v_max3_f32 v3, v3, v118, v119
	v_max3_f32 v2, v2, v117, v100
	v_max3_f32 v3, v3, v102, v103
	v_max3_f32 v2, v2, v101, v120
	v_max3_f32 v3, v3, v122, v123
	v_max3_f32 v2, v2, v121, v104
	v_max3_f32 v3, v3, v106, v107
	v_max3_f32 v2, v2, v105, v124
	v_max3_f32 v3, v3, v126, v127
	v_max3_f32 v2, v2, v125, v108
	v_max3_f32 v3, v3, v110, v111
	v_max3_f32 v2, v2, v109, v3
	v_mov_b32_e32 v3, v2
	s_nop 1
	v_permlane32_swap_b32_e32 v2, v3
	v_max_f32_e32 v2, v2, v3
	v_cmp_lt_f32_e32 vcc, s96, v2
	s_cmp_lg_u64 vcc, 0
	v_add_f32_e32 v231, v212, v4
	s_cselect_b64 s[72:73], -1, 0
	s_cbranch_vccnz .LBB0_291
